# grid barrier: the acquire-side L1 invalidate is issued when the block has arrived (before the arrival atomic) instead of after the release is seen; no L1-allocating loads happen in between
# speedup vs baseline: 1.0429x; 1.0106x over previous
; __device__ __forceinline__ unsigned xb_ld(unsigned* p)              { return __hip_atomic_load(p, __ATOMIC_RELAXED, __HIP_MEMORY_SCOPE_AGENT); }
; __device__ __forceinline__ unsigned xb_add(unsigned* p, unsigned v) { return __hip_atomic_fetch_add(p, v, __ATOMIC_RELAXED, __HIP_MEMORY_SCOPE_AGENT); }
; #define XB_SPIN(cond, bar) do { unsigned _sp = 0; while (cond) { __builtin_amdgcn_s_sleep(1); \
;     if ((++_sp & 255u) == 0u) { if (xb_ld(&(bar)[XB_TMO])) break; if (_sp > XB_SPIN_CAP) { atomicAdd(&(bar)[XB_TMO], 1u); break; } } } } while (0)
; __device__ __forceinline__ void xcd_barrier(const XcdBarrier& b) {
;     ...
;             __builtin_amdgcn_fence(__ATOMIC_RELEASE, "agent");
;             asm volatile("s_waitcnt vmcnt(0)" ::: "memory");
;             const unsigned og = xb_add(&bar[XB_TOP], 1u);
;             const unsigned tg = og / nx;
;             if (og + 1u == (tg + 1u) * nx) xb_add(&bar[XB_TOPGEN], 1u);
;             else XB_SPIN(xb_ld(&bar[XB_TOPGEN]) == tg, bar);
;             __builtin_amdgcn_fence(__ATOMIC_ACQUIRE, "agent");
;             xb_add(&bar[XB_XGEN(b.x)], 1u);
;             asm volatile("s_waitcnt vmcnt(0)" ::: "memory");
.LBB0_278:
	s_or_b64 exec, exec, s[20:21]
	s_waitcnt vmcnt(0)
	s_nop 0
	s_nop 0
	s_nop 0
	s_nop 0
	s_waitcnt vmcnt(0)

; __device__ __forceinline__ unsigned xb_add(unsigned* p, unsigned v) { return __hip_atomic_fetch_add(p, v, __ATOMIC_RELAXED, __HIP_MEMORY_SCOPE_AGENT); }
; __device__ __forceinline__ void xcd_barrier(const XcdBarrier& b) {
;     asm volatile("s_waitcnt vmcnt(0)" ::: "memory");
;     __syncthreads();
;     if (threadIdx.x == 0) {
;         unsigned* bar = b.bar;
;         __builtin_amdgcn_s_waitcnt(0);
;         unsigned nloc = b.st[0], nx = b.st[1];
;         if (nloc == 0u) { xcd_barrier_complete(bar, b.x, nloc, nx); b.st[0] = nloc; b.st[1] = nx; }
;         const unsigned old = xb_add(&bar[XB_XSUB(b.x)], 1u);
.Lmy_pad_Lmyexpskip:
.Lmy_exp_skip:
	s_waitcnt vmcnt(0)
	s_waitcnt vmcnt(0) lgkmcnt(0)
	s_barrier
	s_and_saveexec_b64 s[6:7], s[96:97]
	s_xor_b64 s[36:37], exec, s[6:7]
	s_cbranch_execz .LBB0_414
	v_readlane_b32 s1, v253, 44
	s_waitcnt vmcnt(0) expcnt(0) lgkmcnt(0)
	buffer_inv sc1
	s_nop 0
	v_mov_b32_e32 v0, s1
	ds_read_b32 v3, v0
	v_readlane_b32 s1, v253, 45
	s_waitcnt lgkmcnt(0)
	v_cmp_ne_u32_e32 vcc, 0, v3
	v_mov_b32_e32 v0, s1
	ds_read_b32 v0, v0
	s_cbranch_vccnz .LBB0_381
	s_mov_b32 s1, 1
	s_branch .LBB0_369

; __device__ __forceinline__ unsigned xb_ld(unsigned* p)              { return __hip_atomic_load(p, __ATOMIC_RELAXED, __HIP_MEMORY_SCOPE_AGENT); }
; #define XB_SPIN(cond, bar) do { unsigned _sp = 0; while (cond) { __builtin_amdgcn_s_sleep(1); \
;     if ((++_sp & 255u) == 0u) { if (xb_ld(&(bar)[XB_TMO])) break; if (_sp > XB_SPIN_CAP) { atomicAdd(&(bar)[XB_TMO], 1u); break; } } } } while (0)
; __device__ __forceinline__ void xcd_barrier(const XcdBarrier& b) {
;     ...
;             XB_SPIN(xb_ld(&bar[XB_XGEN(b.x)]) == gen, bar);
;             __builtin_amdgcn_fence(__ATOMIC_ACQUIRE, "agent");
;             asm volatile("s_waitcnt vmcnt(0)" ::: "memory");
.LBB0_394:
	s_or_b64 exec, exec, s[22:23]
	s_waitcnt vmcnt(0)
	s_waitcnt vmcnt(0)

; __device__ __forceinline__ unsigned xb_add(unsigned* p, unsigned v) { return __hip_atomic_fetch_add(p, v, __ATOMIC_RELAXED, __HIP_MEMORY_SCOPE_AGENT); }
; __device__ __forceinline__ void xcd_barrier(const XcdBarrier& b) {
;     ...
;             __builtin_amdgcn_fence(__ATOMIC_ACQUIRE, "agent");
;             xb_add(&bar[XB_XGEN(b.x)], 1u);
;             asm volatile("s_waitcnt vmcnt(0)" ::: "memory");
.LBB0_412:
	s_or_b64 exec, exec, s[22:23]
	s_waitcnt vmcnt(0)
	s_nop 0
	s_nop 0
	s_nop 0
	s_nop 0
	s_waitcnt vmcnt(0)

; __device__ __forceinline__ unsigned xb_add(unsigned* p, unsigned v) { return __hip_atomic_fetch_add(p, v, __ATOMIC_RELAXED, __HIP_MEMORY_SCOPE_AGENT); }
; __device__ __forceinline__ void xcd_barrier(const XcdBarrier& b) {
;     asm volatile("s_waitcnt vmcnt(0)" ::: "memory");
;     __syncthreads();
;     if (threadIdx.x == 0) {
;         unsigned* bar = b.bar;
;         __builtin_amdgcn_s_waitcnt(0);
;         unsigned nloc = b.st[0], nx = b.st[1];
;         if (nloc == 0u) { xcd_barrier_complete(bar, b.x, nloc, nx); b.st[0] = nloc; b.st[1] = nx; }
;         const unsigned old = xb_add(&bar[XB_XSUB(b.x)], 1u);
.LBB0_945:
	s_waitcnt vmcnt(0)
	s_waitcnt lgkmcnt(0)
	s_barrier
	s_and_saveexec_b64 s[4:5], s[96:97]
	s_xor_b64 s[4:5], exec, s[4:5]
	s_cbranch_execz .LBB0_994
	v_readlane_b32 s1, v253, 44
	s_waitcnt vmcnt(0) expcnt(0) lgkmcnt(0)
	buffer_inv sc1
	s_nop 0
	v_mov_b32_e32 v0, s1
	ds_read_b32 v3, v0
	v_readlane_b32 s1, v253, 45
	s_waitcnt lgkmcnt(0)
	v_cmp_ne_u32_e32 vcc, 0, v3
	v_mov_b32_e32 v0, s1
	ds_read_b32 v2, v0
	s_cbranch_vccnz .LBB0_961
	s_mov_b32 s1, 1
	s_branch .LBB0_949

; __device__ __forceinline__ unsigned xb_add(unsigned* p, unsigned v) { return __hip_atomic_fetch_add(p, v, __ATOMIC_RELAXED, __HIP_MEMORY_SCOPE_AGENT); }
; __device__ __forceinline__ void xcd_barrier(const XcdBarrier& b) {
;     asm volatile("s_waitcnt vmcnt(0)" ::: "memory");
;     __syncthreads();
;     if (threadIdx.x == 0) {
;         unsigned* bar = b.bar;
;         __builtin_amdgcn_s_waitcnt(0);
;         unsigned nloc = b.st[0], nx = b.st[1];
;         if (nloc == 0u) { xcd_barrier_complete(bar, b.x, nloc, nx); b.st[0] = nloc; b.st[1] = nx; }
;         const unsigned old = xb_add(&bar[XB_XSUB(b.x)], 1u);
.Lmy_shLBB01065:
.LBB0_1065:
	s_waitcnt vmcnt(0)
	s_waitcnt lgkmcnt(0)
	s_barrier
	s_and_saveexec_b64 s[4:5], s[96:97]
	v_readlane_b32 s14, v253, 53
	v_readlane_b32 s18, v252, 10
	v_readlane_b32 s26, v252, 12
	s_xor_b64 s[4:5], exec, s[4:5]
	v_readlane_b32 s15, v253, 54
	v_readlane_b32 s19, v252, 11
	v_readlane_b32 s27, v252, 13
	s_cbranch_execz .LBB0_1114
	v_readlane_b32 s1, v253, 44
	s_waitcnt vmcnt(0) expcnt(0) lgkmcnt(0)
	buffer_inv sc1
	s_nop 0
	v_mov_b32_e32 v0, s1
	ds_read_b32 v3, v0
	v_readlane_b32 s1, v253, 45
	s_waitcnt lgkmcnt(0)
	v_cmp_ne_u32_e32 vcc, 0, v3
	v_mov_b32_e32 v0, s1
	ds_read_b32 v2, v0
	s_cbranch_vccnz .LBB0_1081
	s_mov_b32 s1, 1
	s_branch .LBB0_1069

; __device__ __forceinline__ unsigned xb_add(unsigned* p, unsigned v) { return __hip_atomic_fetch_add(p, v, __ATOMIC_RELAXED, __HIP_MEMORY_SCOPE_AGENT); }
; __device__ __forceinline__ void xcd_barrier(const XcdBarrier& b) {
;     asm volatile("s_waitcnt vmcnt(0)" ::: "memory");
;     __syncthreads();
;     if (threadIdx.x == 0) {
;         unsigned* bar = b.bar;
;         __builtin_amdgcn_s_waitcnt(0);
;         unsigned nloc = b.st[0], nx = b.st[1];
;         if (nloc == 0u) { xcd_barrier_complete(bar, b.x, nloc, nx); b.st[0] = nloc; b.st[1] = nx; }
;         const unsigned old = xb_add(&bar[XB_XSUB(b.x)], 1u);
.LBB0_1231:
	s_waitcnt vmcnt(0)
	s_waitcnt lgkmcnt(0)
	s_barrier
	s_mov_b64 s[4:5], exec
	v_readlane_b32 s96, v253, 63
	v_readlane_b32 s97, v254, 0
	s_and_b64 s[6:7], s[4:5], s[96:97]
	v_readlane_b32 s82, v254, 4
	v_readlane_b32 s76, v254, 6
	v_readlane_b32 s80, v254, 8
	v_readlane_b32 s34, v253, 53
	v_readlane_b32 s28, v252, 10
	v_readlane_b32 s30, v252, 12
	v_readlane_b32 s66, v253, 55
	v_readlane_b32 s62, v253, 57
	s_xor_b64 s[4:5], s[6:7], s[4:5]
	v_readlane_b32 s78, v254, 2
	v_readlane_b32 s79, v254, 3
	v_readlane_b32 s83, v254, 5
	v_readlane_b32 s77, v254, 7
	v_readlane_b32 s81, v254, 9
	v_readlane_b32 s35, v253, 54
	v_readlane_b32 s29, v252, 11
	v_readlane_b32 s31, v252, 13
	v_readlane_b32 s67, v253, 56
	v_readlane_b32 s63, v253, 58
	v_readlane_b32 s68, v254, 10
	s_movk_i32 s33, 0x2000
	v_readlane_b32 s38, v254, 18
	s_mov_b64 exec, s[6:7]
	s_cbranch_execz .LBB0_1280
	v_readlane_b32 s1, v253, 44
	s_waitcnt vmcnt(0) expcnt(0) lgkmcnt(0)
	buffer_inv sc1
	s_nop 0
	v_mov_b32_e32 v0, s1
	ds_read_b32 v3, v0
	v_readlane_b32 s1, v253, 45
	s_waitcnt lgkmcnt(0)
	v_cmp_ne_u32_e32 vcc, 0, v3
	v_mov_b32_e32 v0, s1
	ds_read_b32 v2, v0
	s_cbranch_vccnz .LBB0_1247
	s_mov_b32 s1, 1
	s_branch .LBB0_1235

; __device__ __forceinline__ unsigned xb_add(unsigned* p, unsigned v) { return __hip_atomic_fetch_add(p, v, __ATOMIC_RELAXED, __HIP_MEMORY_SCOPE_AGENT); }
; __device__ __forceinline__ void xcd_barrier(const XcdBarrier& b) {
;     asm volatile("s_waitcnt vmcnt(0)" ::: "memory");
;     __syncthreads();
;     if (threadIdx.x == 0) {
;         unsigned* bar = b.bar;
;         __builtin_amdgcn_s_waitcnt(0);
;         unsigned nloc = b.st[0], nx = b.st[1];
;         if (nloc == 0u) { xcd_barrier_complete(bar, b.x, nloc, nx); b.st[0] = nloc; b.st[1] = nx; }
;         const unsigned old = xb_add(&bar[XB_XSUB(b.x)], 1u);
.Lmy_shLBB01283:
.LBB0_1283:
	s_waitcnt vmcnt(0)
	s_waitcnt lgkmcnt(0)
	s_barrier
	s_and_saveexec_b64 s[4:5], s[96:97]
	v_readlane_b32 s91, v254, 1
	v_readlane_b32 s75, v254, 11
	v_readlane_b32 s93, v254, 12
	v_readlane_b32 s18, v254, 14
	v_readlane_b32 s19, v254, 15
	s_cbranch_execz .LBB0_1331
	v_readlane_b32 s1, v253, 44
	s_waitcnt vmcnt(0) expcnt(0) lgkmcnt(0)
	buffer_inv sc1
	s_nop 0
	v_mov_b32_e32 v0, s1
	ds_read_b32 v3, v0
	v_readlane_b32 s1, v253, 45
	s_waitcnt lgkmcnt(0)
	v_cmp_ne_u32_e32 vcc, 0, v3
	v_mov_b32_e32 v0, s1
	ds_read_b32 v2, v0
	s_cbranch_vccnz .LBB0_1299
	s_mov_b32 s1, 1
	s_branch .LBB0_1287

; __device__ __forceinline__ unsigned xb_add(unsigned* p, unsigned v) { return __hip_atomic_fetch_add(p, v, __ATOMIC_RELAXED, __HIP_MEMORY_SCOPE_AGENT); }
; __device__ __forceinline__ void xcd_barrier(const XcdBarrier& b) {
;     asm volatile("s_waitcnt vmcnt(0)" ::: "memory");
;     __syncthreads();
;     if (threadIdx.x == 0) {
;         unsigned* bar = b.bar;
;         __builtin_amdgcn_s_waitcnt(0);
;         unsigned nloc = b.st[0], nx = b.st[1];
;         if (nloc == 0u) { xcd_barrier_complete(bar, b.x, nloc, nx); b.st[0] = nloc; b.st[1] = nx; }
;         const unsigned old = xb_add(&bar[XB_XSUB(b.x)], 1u);
.Lmy_shLBB01518:
.LBB0_1518:
	s_waitcnt vmcnt(0)
	s_waitcnt lgkmcnt(0)
	s_barrier
	s_and_saveexec_b64 s[4:5], s[96:97]
	s_xor_b64 s[4:5], exec, s[4:5]
	s_cbranch_execz .LBB0_1567
	v_readlane_b32 s1, v253, 44
	s_waitcnt vmcnt(0) expcnt(0) lgkmcnt(0)
	buffer_inv sc1
	s_nop 0
	v_mov_b32_e32 v0, s1
	ds_read_b32 v3, v0
	v_readlane_b32 s1, v253, 45
	s_waitcnt lgkmcnt(0)
	v_cmp_ne_u32_e32 vcc, 0, v3
	v_mov_b32_e32 v0, s1
	ds_read_b32 v2, v0
	s_cbranch_vccnz .LBB0_1534
	s_mov_b32 s1, 1
	s_branch .LBB0_1522

; __device__ __forceinline__ unsigned xb_add(unsigned* p, unsigned v) { return __hip_atomic_fetch_add(p, v, __ATOMIC_RELAXED, __HIP_MEMORY_SCOPE_AGENT); }
; __device__ __forceinline__ void xcd_barrier(const XcdBarrier& b) {
;     asm volatile("s_waitcnt vmcnt(0)" ::: "memory");
;     __syncthreads();
;     if (threadIdx.x == 0) {
;         unsigned* bar = b.bar;
;         __builtin_amdgcn_s_waitcnt(0);
;         unsigned nloc = b.st[0], nx = b.st[1];
;         if (nloc == 0u) { xcd_barrier_complete(bar, b.x, nloc, nx); b.st[0] = nloc; b.st[1] = nx; }
;         const unsigned old = xb_add(&bar[XB_XSUB(b.x)], 1u);
.LBB0_1594:
	v_readlane_b32 s1, v253, 44
	s_waitcnt vmcnt(0) expcnt(0) lgkmcnt(0)
	buffer_inv sc1
	s_nop 0
	v_mov_b32_e32 v0, s1
	ds_read_b32 v3, v0
	v_readlane_b32 s1, v253, 45
	s_waitcnt lgkmcnt(0)
	v_cmp_ne_u32_e32 vcc, 0, v3
	v_mov_b32_e32 v0, s1
	ds_read_b32 v2, v0
	s_cbranch_vccnz .LBB0_1609
	s_mov_b32 s1, 1
	s_branch .LBB0_1597
